# PV-section LDS reads software-pipelined over 4 register groups (MLA+diff), diff V-tile LDS stride 272->320 B (conflict-free transpose reads)
# speedup vs baseline: 1.0028x; 1.0028x over previous
; __device__ __forceinline__ unsigned cvt_pk_bf16(float lo, float hi) { f32x2 v = {lo, hi}; bf16x2_t b = __builtin_convertvector(v, bf16x2_t); return __builtin_bit_cast(unsigned, b); }
; #define LAS __attribute__((address_space(3)))
; __device__ __forceinline__ float fexp2(float x) { return __builtin_amdgcn_exp2f(x); }
; template <int DK, int DV, int MODE> ...
;     ...
;         mx = fmaxf(mx, __shfl_xor(mx, 32));
;         const float m_new = fmaxf(m, mx), m_use = (m_new == -INFINITY) ? 0.f : m_new;
;         const float alpha = fexp2(m - m_use);
;         float ls = 0.f;
; #pragma unroll
;         for (int i = 0; i < 16; ++i) { p0[i] = fexp2(p0[i] - m_use); p1[i] = fexp2(p1[i] - m_use); ls += p0[i] + p1[i]; }
;         l = l * alpha + ls; m = m_new;
; #pragma unroll
;         for (int d = 0; d < DV / 32; ++d)
; #pragma unroll
;             for (int i = 0; i < 16; ++i) o[d][i] *= alpha;
;         bf16x8 pb[4];
; #pragma unroll
;         for (int sx = 0; sx < 2; ++sx) {
;             u32x4 w0, w1;
;             w0.x = cvt_pk_bf16(p0[8 * sx + 0], p0[8 * sx + 1]); w0.y = cvt_pk_bf16(p0[8 * sx + 2], p0[8 * sx + 3]); w0.z = cvt_pk_bf16(p0[8 * sx + 4], p0[8 * sx + 5]); w0.w = cvt_pk_bf16(p0[8 * sx + 6], p0[8 * sx + 7]);
;             w1.x = cvt_pk_bf16(p1[8 * sx + 0], p1[8 * sx + 1]); w1.y = cvt_pk_bf16(p1[8 * sx + 2], p1[8 * sx + 3]); w1.z = cvt_pk_bf16(p1[8 * sx + 4], p1[8 * sx + 5]); w1.w = cvt_pk_bf16(p1[8 * sx + 6], p1[8 * sx + 7]);
;             pb[sx] = __builtin_bit_cast(bf16x8, w0); pb[2 + sx] = __builtin_bit_cast(bf16x8, w1);
;         }
; #pragma unroll
;         for (int d = 0; d < DV / 32; ++d)
; #pragma unroll
;             for (int t4 = 0; t4 < 4; ++t4) {
;                 const LAS unsigned char* vp_ = Vl + (16 * t4 + 4 * h + ((r & 15) >> 2)) * VSTR + (32 * d + 16 * (r >> 4) + 4 * (r & 3)) * 2;
;                 const s16x4 lo = __builtin_bit_cast(s16x4, __builtin_amdgcn_ds_read_tr16_b64_v4i16((LAS v4i16_t*)vp_));
;                 const s16x4 hi = __builtin_bit_cast(s16x4, __builtin_amdgcn_ds_read_tr16_b64_v4i16((LAS v4i16_t*)(vp_ + 8 * VSTR)));
;                 const bf16x8 vf = __builtin_shufflevector(lo, hi, 0, 1, 2, 3, 4, 5, 6, 7);
;                 o[d] = MFMA32(vf, pb[t4], o[d]);
;                 if (DV > 64 && t4 == 3) __builtin_amdgcn_sched_barrier(0);
;             }
.Ljoin_nm0:
	ds_bpermute_b32 v36, v190, v35
	v_mov_b32_e32 v37, v0
	s_waitcnt lgkmcnt(0)
	v_max3_f32 v50, v175, v35, v36
	v_cmp_neq_f32_e32 vcc, s88, v50
	s_nop 1
	v_cndmask_b32_e32 v209, 0, v50, vcc
	v_sub_f32_e32 v34, v34, v209
	v_exp_f32_e32 v210, v34
	v_sub_f32_e32 v34, v178, v209
	v_exp_f32_e32 v211, v34
	v_sub_f32_e32 v34, v177, v209
	v_exp_f32_e32 v36, v34
	v_sub_f32_e32 v34, v51, v209
	v_exp_f32_e32 v34, v34
	v_add_f32_e32 v35, v211, v210
	v_sub_f32_e32 v40, v53, v209
	v_exp_f32_e32 v40, v40
	v_pk_add_f32 v[38:39], v[34:35], v[36:37]
	v_sub_f32_e32 v35, v179, v209
	v_pk_add_f32 v[38:39], v[38:39], v[38:39] op_sel_hi:[0,1]
	v_sub_f32_e32 v37, v52, v209
	v_exp_f32_e32 v35, v35
	v_exp_f32_e32 v37, v37
	v_sub_f32_e32 v38, v180, v209
	v_exp_f32_e32 v38, v38
	v_sub_f32_e32 v44, v55, v209
	v_add_f32_e32 v41, v37, v35
	v_exp_f32_e32 v44, v44
	v_pk_add_f32 v[42:43], v[40:41], v[38:39]
	v_sub_f32_e32 v39, v181, v209
	v_pk_add_f32 v[42:43], v[42:43], v[42:43] op_sel_hi:[0,1]
	v_sub_f32_e32 v41, v54, v209
	v_exp_f32_e32 v39, v39
	v_exp_f32_e32 v41, v41
	v_sub_f32_e32 v42, v182, v209
	v_exp_f32_e32 v42, v42
	v_sub_f32_e32 v175, v175, v209
	v_add_f32_e32 v45, v41, v39
	v_pk_add_f32 v[46:47], v[44:45], v[42:43]
	s_nop 0
	v_pk_add_f32 v[52:53], v[46:47], v[46:47] op_sel_hi:[0,1]
	v_sub_f32_e32 v43, v183, v209
	v_sub_f32_e32 v45, v56, v209
	v_sub_f32_e32 v46, v184, v209
	v_exp_f32_e32 v43, v43
	v_exp_f32_e32 v45, v45
	v_exp_f32_e32 v52, v46
	v_sub_f32_e32 v46, v57, v209
	v_exp_f32_e32 v54, v46
	v_add_f32_e32 v55, v45, v43
	v_pk_add_f32 v[46:47], v[54:55], v[52:53]
	s_nop 0
	v_pk_add_f32 v[56:57], v[46:47], v[46:47] op_sel_hi:[0,1]
	v_sub_f32_e32 v46, v185, v209
	v_exp_f32_e32 v53, v46
	v_sub_f32_e32 v46, v58, v209
	v_exp_f32_e32 v55, v46
	v_sub_f32_e32 v46, v198, v209
	v_exp_f32_e32 v56, v46
	v_sub_f32_e32 v46, v197, v209
	v_exp_f32_e32 v58, v46
	v_add_f32_e32 v59, v55, v53
	v_pk_add_f32 v[46:47], v[58:59], v[56:57]
	s_nop 0
	v_pk_add_f32 v[60:61], v[46:47], v[46:47] op_sel_hi:[0,1]
	v_sub_f32_e32 v46, v200, v209
	v_exp_f32_e32 v57, v46
	v_sub_f32_e32 v46, v199, v209
	v_exp_f32_e32 v59, v46
	v_sub_f32_e32 v46, v202, v209
	v_exp_f32_e32 v60, v46
	v_sub_f32_e32 v46, v201, v209
	v_exp_f32_e32 v62, v46
	v_add_f32_e32 v63, v59, v57
	v_pk_add_f32 v[46:47], v[62:63], v[60:61]
	s_nop 0
	v_pk_add_f32 v[64:65], v[46:47], v[46:47] op_sel_hi:[0,1]
	v_sub_f32_e32 v46, v204, v209
	v_exp_f32_e32 v61, v46
	v_sub_f32_e32 v46, v203, v209
	v_exp_f32_e32 v63, v46
	v_sub_f32_e32 v46, v206, v209
	v_exp_f32_e32 v64, v46
	v_sub_f32_e32 v46, v205, v209
	v_exp_f32_e32 v176, v46
	v_add_f32_e32 v177, v63, v61
	v_pk_add_f32 v[46:47], v[176:177], v[64:65]
	s_nop 0
	v_pk_add_f32 v[178:179], v[46:47], v[46:47] op_sel_hi:[0,1]
	v_sub_f32_e32 v46, v207, v209
	v_exp_f32_e32 v65, v46
	v_sub_f32_e32 v46, v48, v209
	v_exp_f32_e32 v177, v46
	v_sub_f32_e32 v46, v208, v209
	v_exp_f32_e32 v178, v46
	v_sub_f32_e32 v46, v49, v209
	v_exp_f32_e32 v180, v46
	v_add_f32_e32 v181, v177, v65
	v_cvt_pk_bf16_f32 v48, v39, v42
	v_cvt_pk_bf16_f32 v42, v53, v56
	v_pk_add_f32 v[46:47], v[180:181], v[178:179]
	v_add_u32_e32 v56, v191, v129
	v_add_f32_e32 v51, v46, v47
	v_exp_f32_e32 v46, v175
	v_cvt_pk_bf16_f32 v49, v43, v52
	v_cvt_pk_bf16_f32 v39, v37, v40
	v_cvt_pk_bf16_f32 v40, v41, v44
	v_pk_mul_f32 v[18:19], v[18:19], v[46:47] op_sel_hi:[1,0]
	v_pk_mul_f32 v[20:21], v[20:21], v[46:47] op_sel_hi:[1,0]
	v_pk_mul_f32 v[22:23], v[22:23], v[46:47] op_sel_hi:[1,0]
	v_pk_mul_f32 v[24:25], v[24:25], v[46:47] op_sel_hi:[1,0]
	v_pk_mul_f32 v[26:27], v[26:27], v[46:47] op_sel_hi:[1,0]
	v_pk_mul_f32 v[28:29], v[28:29], v[46:47] op_sel_hi:[1,0]
	v_pk_mul_f32 v[30:31], v[30:31], v[46:47] op_sel_hi:[1,0]
	v_pk_mul_f32 v[32:33], v[32:33], v[46:47] op_sel_hi:[1,0]
	v_pk_mul_f32 v[2:3], v[2:3], v[46:47] op_sel_hi:[1,0]
	v_pk_mul_f32 v[4:5], v[4:5], v[46:47] op_sel_hi:[1,0]
	v_pk_mul_f32 v[6:7], v[6:7], v[46:47] op_sel_hi:[1,0]
	v_pk_mul_f32 v[8:9], v[8:9], v[46:47] op_sel_hi:[1,0]
	v_pk_mul_f32 v[10:11], v[10:11], v[46:47] op_sel_hi:[1,0]
	v_pk_mul_f32 v[12:13], v[12:13], v[46:47] op_sel_hi:[1,0]
	v_pk_mul_f32 v[14:15], v[14:15], v[46:47] op_sel_hi:[1,0]
	v_pk_mul_f32 v[16:17], v[16:17], v[46:47] op_sel_hi:[1,0]
	v_cvt_pk_bf16_f32 v47, v35, v38
	v_cvt_pk_bf16_f32 v38, v211, v34
	v_cvt_pk_bf16_f32 v41, v45, v54
	v_cvt_pk_bf16_f32 v34, v55, v58
	v_fmac_f32_e32 v51, v174, v46
	v_cvt_pk_bf16_f32 v46, v210, v36
	v_cvt_pk_bf16_f32 v43, v57, v60
	v_cvt_pk_bf16_f32 v44, v61, v64
	v_cvt_pk_bf16_f32 v45, v65, v178
	v_cvt_pk_bf16_f32 v35, v59, v62
	v_cvt_pk_bf16_f32 v36, v63, v176
	v_cvt_pk_bf16_f32 v37, v177, v180
	v_mov_b32_e32 v175, v50
	v_mov_b32_e32 v174, v51
	ds_read_b64_tr_b16 v[176:177], v56 offset:13312
	ds_read_b64_tr_b16 v[178:179], v56 offset:14464
	ds_read_b64_tr_b16 v[180:181], v56 offset:15616
	ds_read_b64_tr_b16 v[182:183], v56 offset:16768
	ds_read_b64_tr_b16 v[198:199], v56 offset:17920
	ds_read_b64_tr_b16 v[200:201], v56 offset:19072
	ds_read_b64_tr_b16 v[202:203], v56 offset:20224
	ds_read_b64_tr_b16 v[204:205], v56 offset:21376
	s_waitcnt lgkmcnt(6)
	v_mfma_f32_32x32x16_bf16 v[18:33], v[176:179], v[46:49], v[18:33]
	ds_read_b64_tr_b16 v[176:177], v56 offset:13376
	ds_read_b64_tr_b16 v[178:179], v56 offset:14528
	s_waitcnt lgkmcnt(6)
	v_mfma_f32_32x32x16_bf16 v[18:33], v[180:183], v[42:45], v[18:33]
	ds_read_b64_tr_b16 v[180:181], v56 offset:15680
	ds_read_b64_tr_b16 v[182:183], v56 offset:16832
	s_waitcnt lgkmcnt(6)
	v_mfma_f32_32x32x16_bf16 v[18:33], v[198:201], v[38:41], v[18:33]
	ds_read_b64_tr_b16 v[198:199], v56 offset:17984
	ds_read_b64_tr_b16 v[200:201], v56 offset:19136
	s_waitcnt lgkmcnt(6)
	v_mfma_f32_32x32x16_bf16 v[18:33], v[202:205], v[34:37], v[18:33]
	ds_read_b64_tr_b16 v[202:203], v56 offset:20288
	ds_read_b64_tr_b16 v[204:205], v56 offset:21440
	s_waitcnt lgkmcnt(6)
	v_mfma_f32_32x32x16_bf16 v[2:17], v[176:179], v[46:49], v[2:17]
	s_waitcnt lgkmcnt(4)
	v_mfma_f32_32x32x16_bf16 v[2:17], v[180:183], v[42:45], v[2:17]
	s_waitcnt lgkmcnt(2)
	v_mfma_f32_32x32x16_bf16 v[2:17], v[198:201], v[38:41], v[2:17]
	s_waitcnt lgkmcnt(0)
	v_mfma_f32_32x32x16_bf16 v[2:17], v[202:205], v[34:37], v[2:17]
	s_or_b64 exec, exec, s[54:55]
	s_add_i32 s26, s62, -2
	s_cmp_ge_u32 s26, s53
	s_cbranch_scc1 .LBB0_571

; __device__ __forceinline__ unsigned cvt_pk_bf16(float lo, float hi) { f32x2 v = {lo, hi}; bf16x2_t b = __builtin_convertvector(v, bf16x2_t); return __builtin_bit_cast(unsigned, b); }
; #define LAS __attribute__((address_space(3)))
; __device__ __forceinline__ float fexp2(float x) { return __builtin_amdgcn_exp2f(x); }
; template <int DK, int DV, int MODE> ...
;     ...
;         mx = fmaxf(mx, __shfl_xor(mx, 32));
;         const float m_new = fmaxf(m, mx), m_use = (m_new == -INFINITY) ? 0.f : m_new;
;         const float alpha = fexp2(m - m_use);
;         float ls = 0.f;
; #pragma unroll
;         for (int i = 0; i < 16; ++i) { p0[i] = fexp2(p0[i] - m_use); p1[i] = fexp2(p1[i] - m_use); ls += p0[i] + p1[i]; }
;         l = l * alpha + ls; m = m_new;
; #pragma unroll
;         for (int d = 0; d < DV / 32; ++d)
; #pragma unroll
;             for (int i = 0; i < 16; ++i) o[d][i] *= alpha;
;         bf16x8 pb[4];
; #pragma unroll
;         for (int sx = 0; sx < 2; ++sx) {
;             u32x4 w0, w1;
;             w0.x = cvt_pk_bf16(p0[8 * sx + 0], p0[8 * sx + 1]); w0.y = cvt_pk_bf16(p0[8 * sx + 2], p0[8 * sx + 3]); w0.z = cvt_pk_bf16(p0[8 * sx + 4], p0[8 * sx + 5]); w0.w = cvt_pk_bf16(p0[8 * sx + 6], p0[8 * sx + 7]);
;             w1.x = cvt_pk_bf16(p1[8 * sx + 0], p1[8 * sx + 1]); w1.y = cvt_pk_bf16(p1[8 * sx + 2], p1[8 * sx + 3]); w1.z = cvt_pk_bf16(p1[8 * sx + 4], p1[8 * sx + 5]); w1.w = cvt_pk_bf16(p1[8 * sx + 6], p1[8 * sx + 7]);
;             pb[sx] = __builtin_bit_cast(bf16x8, w0); pb[2 + sx] = __builtin_bit_cast(bf16x8, w1);
;         }
; #pragma unroll
;         for (int d = 0; d < DV / 32; ++d)
; #pragma unroll
;             for (int t4 = 0; t4 < 4; ++t4) {
;                 const LAS unsigned char* vp_ = Vl + (16 * t4 + 4 * h + ((r & 15) >> 2)) * VSTR + (32 * d + 16 * (r >> 4) + 4 * (r & 3)) * 2;
;                 const s16x4 lo = __builtin_bit_cast(s16x4, __builtin_amdgcn_ds_read_tr16_b64_v4i16((LAS v4i16_t*)vp_));
;                 const s16x4 hi = __builtin_bit_cast(s16x4, __builtin_amdgcn_ds_read_tr16_b64_v4i16((LAS v4i16_t*)(vp_ + 8 * VSTR)));
;                 const bf16x8 vf = __builtin_shufflevector(lo, hi, 0, 1, 2, 3, 4, 5, 6, 7);
;                 o[d] = MFMA32(vf, pb[t4], o[d]);
;                 if (DV > 64 && t4 == 3) __builtin_amdgcn_sched_barrier(0);
;             }
.Ljoin_nm1:
	ds_bpermute_b32 v36, v190, v35
	v_mov_b32_e32 v37, v0
	s_waitcnt lgkmcnt(0)
	v_max3_f32 v50, v175, v35, v36
	v_cmp_neq_f32_e32 vcc, s88, v50
	s_nop 1
	v_cndmask_b32_e32 v209, 0, v50, vcc
	v_sub_f32_e32 v34, v34, v209
	v_exp_f32_e32 v210, v34
	v_sub_f32_e32 v34, v178, v209
	v_exp_f32_e32 v211, v34
	v_sub_f32_e32 v34, v177, v209
	v_exp_f32_e32 v36, v34
	v_sub_f32_e32 v34, v51, v209
	v_exp_f32_e32 v34, v34
	v_add_f32_e32 v35, v211, v210
	v_sub_f32_e32 v40, v53, v209
	v_exp_f32_e32 v40, v40
	v_pk_add_f32 v[38:39], v[34:35], v[36:37]
	v_sub_f32_e32 v35, v179, v209
	v_pk_add_f32 v[38:39], v[38:39], v[38:39] op_sel_hi:[0,1]
	v_sub_f32_e32 v37, v52, v209
	v_exp_f32_e32 v35, v35
	v_exp_f32_e32 v37, v37
	v_sub_f32_e32 v38, v180, v209
	v_exp_f32_e32 v38, v38
	v_sub_f32_e32 v44, v55, v209
	v_add_f32_e32 v41, v37, v35
	v_exp_f32_e32 v44, v44
	v_pk_add_f32 v[42:43], v[40:41], v[38:39]
	v_sub_f32_e32 v39, v181, v209
	v_pk_add_f32 v[42:43], v[42:43], v[42:43] op_sel_hi:[0,1]
	v_sub_f32_e32 v41, v54, v209
	v_exp_f32_e32 v39, v39
	v_exp_f32_e32 v41, v41
	v_sub_f32_e32 v42, v182, v209
	v_exp_f32_e32 v42, v42
	v_sub_f32_e32 v175, v175, v209
	v_add_f32_e32 v45, v41, v39
	v_pk_add_f32 v[46:47], v[44:45], v[42:43]
	s_nop 0
	v_pk_add_f32 v[52:53], v[46:47], v[46:47] op_sel_hi:[0,1]
	v_sub_f32_e32 v43, v183, v209
	v_sub_f32_e32 v45, v56, v209
	v_sub_f32_e32 v46, v184, v209
	v_exp_f32_e32 v43, v43
	v_exp_f32_e32 v45, v45
	v_exp_f32_e32 v52, v46
	v_sub_f32_e32 v46, v57, v209
	v_exp_f32_e32 v54, v46
	v_add_f32_e32 v55, v45, v43
	v_pk_add_f32 v[46:47], v[54:55], v[52:53]
	s_nop 0
	v_pk_add_f32 v[56:57], v[46:47], v[46:47] op_sel_hi:[0,1]
	v_sub_f32_e32 v46, v185, v209
	v_exp_f32_e32 v53, v46
	v_sub_f32_e32 v46, v58, v209
	v_exp_f32_e32 v55, v46
	v_sub_f32_e32 v46, v198, v209
	v_exp_f32_e32 v56, v46
	v_sub_f32_e32 v46, v197, v209
	v_exp_f32_e32 v58, v46
	v_add_f32_e32 v59, v55, v53
	v_pk_add_f32 v[46:47], v[58:59], v[56:57]
	s_nop 0
	v_pk_add_f32 v[60:61], v[46:47], v[46:47] op_sel_hi:[0,1]
	v_sub_f32_e32 v46, v200, v209
	v_exp_f32_e32 v57, v46
	v_sub_f32_e32 v46, v199, v209
	v_exp_f32_e32 v59, v46
	v_sub_f32_e32 v46, v202, v209
	v_exp_f32_e32 v60, v46
	v_sub_f32_e32 v46, v201, v209
	v_exp_f32_e32 v62, v46
	v_add_f32_e32 v63, v59, v57
	v_pk_add_f32 v[46:47], v[62:63], v[60:61]
	s_nop 0
	v_pk_add_f32 v[64:65], v[46:47], v[46:47] op_sel_hi:[0,1]
	v_sub_f32_e32 v46, v204, v209
	v_exp_f32_e32 v61, v46
	v_sub_f32_e32 v46, v203, v209
	v_exp_f32_e32 v63, v46
	v_sub_f32_e32 v46, v206, v209
	v_exp_f32_e32 v64, v46
	v_sub_f32_e32 v46, v205, v209
	v_exp_f32_e32 v176, v46
	v_add_f32_e32 v177, v63, v61
	v_pk_add_f32 v[46:47], v[176:177], v[64:65]
	s_nop 0
	v_pk_add_f32 v[178:179], v[46:47], v[46:47] op_sel_hi:[0,1]
	v_sub_f32_e32 v46, v207, v209
	v_exp_f32_e32 v65, v46
	v_sub_f32_e32 v46, v48, v209
	v_exp_f32_e32 v177, v46
	v_sub_f32_e32 v46, v208, v209
	v_exp_f32_e32 v178, v46
	v_sub_f32_e32 v46, v49, v209
	v_exp_f32_e32 v180, v46
	v_add_f32_e32 v181, v177, v65
	v_cvt_pk_bf16_f32 v48, v39, v42
	v_cvt_pk_bf16_f32 v42, v53, v56
	v_pk_add_f32 v[46:47], v[180:181], v[178:179]
	v_add_u32_e32 v56, v191, v129
	v_add_f32_e32 v51, v46, v47
	v_exp_f32_e32 v46, v175
	v_cvt_pk_bf16_f32 v49, v43, v52
	v_cvt_pk_bf16_f32 v39, v37, v40
	v_cvt_pk_bf16_f32 v40, v41, v44
	v_pk_mul_f32 v[18:19], v[18:19], v[46:47] op_sel_hi:[1,0]
	v_pk_mul_f32 v[20:21], v[20:21], v[46:47] op_sel_hi:[1,0]
	v_pk_mul_f32 v[22:23], v[22:23], v[46:47] op_sel_hi:[1,0]
	v_pk_mul_f32 v[24:25], v[24:25], v[46:47] op_sel_hi:[1,0]
	v_pk_mul_f32 v[26:27], v[26:27], v[46:47] op_sel_hi:[1,0]
	v_pk_mul_f32 v[28:29], v[28:29], v[46:47] op_sel_hi:[1,0]
	v_pk_mul_f32 v[30:31], v[30:31], v[46:47] op_sel_hi:[1,0]
	v_pk_mul_f32 v[32:33], v[32:33], v[46:47] op_sel_hi:[1,0]
	v_pk_mul_f32 v[2:3], v[2:3], v[46:47] op_sel_hi:[1,0]
	v_pk_mul_f32 v[4:5], v[4:5], v[46:47] op_sel_hi:[1,0]
	v_pk_mul_f32 v[6:7], v[6:7], v[46:47] op_sel_hi:[1,0]
	v_pk_mul_f32 v[8:9], v[8:9], v[46:47] op_sel_hi:[1,0]
	v_pk_mul_f32 v[10:11], v[10:11], v[46:47] op_sel_hi:[1,0]
	v_pk_mul_f32 v[12:13], v[12:13], v[46:47] op_sel_hi:[1,0]
	v_pk_mul_f32 v[14:15], v[14:15], v[46:47] op_sel_hi:[1,0]
	v_pk_mul_f32 v[16:17], v[16:17], v[46:47] op_sel_hi:[1,0]
	v_cvt_pk_bf16_f32 v47, v35, v38
	v_cvt_pk_bf16_f32 v38, v211, v34
	v_cvt_pk_bf16_f32 v41, v45, v54
	v_cvt_pk_bf16_f32 v34, v55, v58
	v_fmac_f32_e32 v51, v174, v46
	v_cvt_pk_bf16_f32 v46, v210, v36
	v_cvt_pk_bf16_f32 v43, v57, v60
	v_cvt_pk_bf16_f32 v44, v61, v64
	v_cvt_pk_bf16_f32 v45, v65, v178
	v_cvt_pk_bf16_f32 v35, v59, v62
	v_cvt_pk_bf16_f32 v36, v63, v176
	v_cvt_pk_bf16_f32 v37, v177, v180
	v_mov_b32_e32 v174, v51
	v_mov_b32_e32 v175, v50
	ds_read_b64_tr_b16 v[52:53], v56 offset:35840
	ds_read_b64_tr_b16 v[54:55], v56 offset:36992
	ds_read_b64_tr_b16 v[58:59], v56 offset:38144
	ds_read_b64_tr_b16 v[60:61], v56 offset:39296
	ds_read_b64_tr_b16 v[62:63], v56 offset:40448
	ds_read_b64_tr_b16 v[64:65], v56 offset:41600
	ds_read_b64_tr_b16 v[176:177], v56 offset:42752
	ds_read_b64_tr_b16 v[178:179], v56 offset:43904
	s_waitcnt lgkmcnt(6)
	v_mfma_f32_32x32x16_bf16 v[18:33], v[52:55], v[46:49], v[18:33]
	ds_read_b64_tr_b16 v[52:53], v56 offset:35904
	ds_read_b64_tr_b16 v[54:55], v56 offset:37056
	s_waitcnt lgkmcnt(6)
	v_mfma_f32_32x32x16_bf16 v[18:33], v[58:61], v[42:45], v[18:33]
	ds_read_b64_tr_b16 v[58:59], v56 offset:38208
	ds_read_b64_tr_b16 v[60:61], v56 offset:39360
	s_waitcnt lgkmcnt(6)
	v_mfma_f32_32x32x16_bf16 v[18:33], v[62:65], v[38:41], v[18:33]
	ds_read_b64_tr_b16 v[62:63], v56 offset:40512
	ds_read_b64_tr_b16 v[64:65], v56 offset:41664
	s_waitcnt lgkmcnt(6)
	v_mfma_f32_32x32x16_bf16 v[18:33], v[176:179], v[34:37], v[18:33]
	ds_read_b64_tr_b16 v[176:177], v56 offset:42816
	ds_read_b64_tr_b16 v[178:179], v56 offset:43968
	s_waitcnt lgkmcnt(6)
	v_mfma_f32_32x32x16_bf16 v[2:17], v[52:55], v[46:49], v[2:17]
	s_waitcnt lgkmcnt(4)
	v_mfma_f32_32x32x16_bf16 v[2:17], v[58:61], v[42:45], v[2:17]
	s_waitcnt lgkmcnt(2)
	v_mfma_f32_32x32x16_bf16 v[2:17], v[62:65], v[38:41], v[2:17]
	s_waitcnt lgkmcnt(0)
	v_mfma_f32_32x32x16_bf16 v[2:17], v[176:179], v[34:37], v[2:17]

; __global__ void __launch_bounds__(NTHREADS, 2) hybrid_fwd(Params P) {
;     ...
;             const float lam = __expf(wave_sum(PL->in[I_LQ1][lane] * PL->in[I_LK1][lane])) - __expf(wave_sum(PL->in[I_LQ2][lane] * PL->in[I_LK2][lane])) + LAMBDA_INIT;
;             if (EN(12)) for (int un = vb; un < NB * 8 * 8; un += G) {
;                 int bh, qb;
;                 if (G == 256) { const int i = un >> 8; bh = vb >> 2; qb = i == 0 ? (vb & 3) : 7 - (vb & 3); }
;                 else { bh = un >> 3; qb = un & 7; }
;                 const int b = bh >> 3, hd = bh & 7;
;                 AttSrc s; s.qp = CDP; s.kap = CDP; s.kbp = CDP; s.SK = SEQ; s.v = u + (size_t)b * SEQ * CDP + 2848 + hd * 128; s.vp = CDP;
;                 s.q = u + (size_t)b * SEQ * CDP + 800 + (2 * hd) * 64; s.ka = u + (size_t)b * SEQ * CDP + 1824 + (2 * hd) * 64; s.kb = s.ka;
;                 f32x16 o1[4];
;                 f32x4* stash = (f32x4*)(ws + WS_XB) + (size_t)bx * NTHREADS + tid;
.LBB0_574:
	v_readlane_b32 s1, v254, 39
	v_and_b32_e32 v2, 63, v116
	v_lshlrev_b32_e32 v8, 2, v2
	v_mov_b32_e32 v4, s1
	ds_read_b128 v[4:7], v4
	v_mov_b32_e32 v9, v0
	v_readlane_b32 s1, v254, 40
	s_cmpk_gt_i32 s2, 0x1ff
	s_waitcnt lgkmcnt(0)
	v_lshl_add_u64 v[4:5], v[4:5], 0, v[8:9]
	flat_load_dword v2, v[4:5]
	v_lshl_add_u64 v[4:5], v[6:7], 0, v[8:9]
	flat_load_dword v4, v[4:5]
	v_xor_b32_e32 v6, 1, v3
	v_cmp_lt_i32_e32 vcc, v6, v189
	s_waitcnt vmcnt(0) lgkmcnt(0)
	v_mul_f32_e32 v5, v2, v4
	v_cndmask_b32_e32 v6, v3, v6, vcc
	v_lshlrev_b32_e32 v10, 2, v6
	ds_bpermute_b32 v5, v10, v5
	s_waitcnt lgkmcnt(0)
	v_fmac_f32_e32 v5, v2, v4
	v_xor_b32_e32 v2, 2, v3
	v_cmp_lt_i32_e32 vcc, v2, v189
	v_xor_b32_e32 v4, 4, v3
	s_nop 0
	v_cndmask_b32_e32 v2, v3, v2, vcc
	v_lshlrev_b32_e32 v11, 2, v2
	ds_bpermute_b32 v2, v11, v5
	v_cmp_lt_i32_e32 vcc, v4, v189
	s_waitcnt lgkmcnt(0)
	v_add_f32_e32 v2, v5, v2
	v_cndmask_b32_e32 v4, v3, v4, vcc
	v_lshlrev_b32_e32 v12, 2, v4
	ds_bpermute_b32 v4, v12, v2
	s_waitcnt lgkmcnt(0)
	v_add_f32_e32 v2, v2, v4
	v_xor_b32_e32 v4, 8, v3
	v_cmp_lt_i32_e32 vcc, v4, v189
	s_nop 1
	v_cndmask_b32_e32 v4, v3, v4, vcc
	v_lshlrev_b32_e32 v13, 2, v4
	ds_bpermute_b32 v4, v13, v2
	s_waitcnt lgkmcnt(0)
	v_add_f32_e32 v2, v2, v4
	v_xor_b32_e32 v4, 16, v3
	v_cmp_lt_i32_e32 vcc, v4, v189
	s_nop 1
	v_cndmask_b32_e32 v4, v3, v4, vcc
	v_lshlrev_b32_e32 v14, 2, v4
	ds_bpermute_b32 v4, v14, v2
	v_cmp_lt_i32_e32 vcc, v188, v189
	s_waitcnt lgkmcnt(0)
	v_add_f32_e32 v2, v2, v4
	v_mov_b32_e32 v4, s1
	ds_read_b128 v[4:7], v4
	v_cndmask_b32_e32 v3, v3, v188, vcc
	v_lshlrev_b32_e32 v165, 2, v3
	ds_bpermute_b32 v3, v165, v2
	s_waitcnt lgkmcnt(1)
	v_lshl_add_u64 v[4:5], v[4:5], 0, v[8:9]
	flat_load_dword v15, v[4:5]
	v_lshl_add_u64 v[4:5], v[6:7], 0, v[8:9]
	flat_load_dword v4, v[4:5]
	s_waitcnt vmcnt(0) lgkmcnt(0)
	v_mul_f32_e32 v5, v15, v4
	ds_bpermute_b32 v5, v10, v5
	s_waitcnt lgkmcnt(0)
	v_fmac_f32_e32 v5, v15, v4
	ds_bpermute_b32 v4, v11, v5
	s_waitcnt lgkmcnt(0)
	v_add_f32_e32 v4, v5, v4
	ds_bpermute_b32 v5, v12, v4
	s_waitcnt lgkmcnt(0)
	v_add_f32_e32 v4, v4, v5
	ds_bpermute_b32 v5, v13, v4
	s_waitcnt lgkmcnt(0)
	v_add_f32_e32 v4, v4, v5
	ds_bpermute_b32 v5, v14, v4
	s_waitcnt lgkmcnt(0)
	v_add_f32_e32 v4, v4, v5
	ds_bpermute_b32 v5, v165, v4
	s_cbranch_scc1 .LBB0_605
	v_add_f32_e32 v2, v2, v3
	s_waitcnt lgkmcnt(0)
	v_add_f32_e32 v3, v4, v5
	v_mul_f32_e32 v2, 0x3fb8aa3b, v2
	v_mul_f32_e32 v3, 0x3fb8aa3b, v3
	v_exp_f32_e32 v2, v2
	v_exp_f32_e32 v3, v3
	s_cmpk_eq_i32 s0, 0x100
	s_cselect_b64 s[16:17], -1, 0
	s_and_b32 s33, s2, 3
	s_ashr_i32 s9, s8, 31
	s_ashr_i32 s27, s2, 2
	s_xor_b32 s34, s33, 7
	s_lshl_b64 s[8:9], s[8:9], 13
	s_add_u32 s8, s4, s8
	v_sub_f32_e32 v2, v2, v3
	s_addc_u32 s9, s5, s9
	v_add_f32_e32 v140, 0x3eb60549, v2
	v_lshl_add_u64 v[2:3], v[116:117], 4, s[8:9]
	s_mov_b64 s[8:9], 0xe000000
	v_lshl_add_u64 v[142:143], v[2:3], 0, s[8:9]
	v_add_u32_e32 v2, v116, v187
	v_ashrrev_i32_e32 v148, 3, v2
	v_ashrrev_i32_e32 v149, 31, v148
	v_and_b32_e32 v2, -8, v2
	v_lshlrev_b64 v[150:151], 13, v[148:149]
	v_sub_u32_e32 v149, v116, v2
	v_lshrrev_b32_e32 v2, 28, v117
	v_add_u32_e32 v3, v116, v2
	v_ashrrev_i32_e32 v2, 4, v3
	v_and_b32_e32 v3, -16, v3
	v_sub_u32_e32 v6, v116, v3
	v_ashrrev_i32_e32 v3, 31, v2
	v_lshlrev_b64 v[154:155], 13, v[2:3]
	v_ashrrev_i32_e32 v3, 31, v186
	s_movk_i32 s1, 0x200
	v_lshrrev_b32_e32 v3, 28, v3
	v_cmp_gt_i32_e64 s[38:39], s1, v116
	s_movk_i32 s1, 0x1ff
	v_add_u32_e32 v3, v186, v3
	v_cmp_lt_i32_e64 s[40:41], s1, v116
	v_ashrrev_i32_e32 v4, 4, v3
	s_movk_i32 s1, 0x140
	v_mul_lo_u32 v230, v2, s1
	v_mul_lo_u32 v232, v4, s1
	s_ashr_i32 s1, s0, 31
	s_lshl_b64 s[8:9], s[0:1], 13
	v_lshl_add_u64 v[166:167], v[142:143], 0, s[8:9]
	v_lshl_add_u64 v[168:169], v[166:167], 0, s[8:9]
	v_lshl_add_u64 v[170:171], v[168:169], 0, s[8:9]
	v_lshl_add_u64 v[172:173], v[170:171], 0, s[8:9]
	v_lshl_add_u64 v[174:175], v[172:173], 0, s[8:9]
	v_lshl_add_u64 v[176:177], v[174:175], 0, s[8:9]
	v_lshl_add_u64 v[178:179], v[176:177], 0, s[8:9]
	v_lshl_add_u64 v[180:181], v[178:179], 0, s[8:9]
	v_lshl_add_u64 v[182:183], v[180:181], 0, s[8:9]
	v_and_b32_e32 v3, -16, v3
	v_lshl_add_u64 v[184:185], v[182:183], 0, s[8:9]
	v_sub_u32_e32 v3, v186, v3
	v_lshl_add_u64 v[186:187], v[184:185], 0, s[8:9]
	v_lshl_add_u64 v[188:189], v[186:187], 0, s[8:9]
	s_lshl_b32 s1, s25, 5
	v_lshl_add_u64 v[190:191], v[188:189], 0, s[8:9]
	s_ashr_i32 s12, s1, 31
	v_lshl_add_u64 v[192:193], v[190:191], 0, s[8:9]
	v_lshl_add_u64 v[194:195], v[192:193], 0, s[8:9]
	s_add_u32 s8, s4, 0x12080e40
	v_ashrrev_i32_e32 v5, 31, v4
	v_lshlrev_b32_e32 v160, 3, v3
	s_addc_u32 s9, s5, 0
	v_lshlrev_b32_e32 v156, 3, v6
	v_lshlrev_b64 v[158:159], 13, v[4:5]
	v_ashrrev_i32_e32 v161, 31, v160
	s_add_u32 s36, s4, 0x12081640
	v_ashrrev_i32_e32 v157, 31, v156
	v_lshlrev_b32_e32 v233, 4, v3
	s_addc_u32 s37, s5, 0
	v_lshl_add_u64 v[2:3], v[160:161], 1, v[158:159]
	v_lshrrev_b32_e32 v144, 3, v116
	v_and_b32_e32 v226, 7, v116
	v_lshlrev_b32_e32 v152, 3, v149
	v_and_or_b32 v1, v1, 3, v225
	v_lshl_add_u64 v[196:197], s[36:37], 0, v[2:3]
	v_lshl_add_u64 v[2:3], v[156:157], 1, v[154:155]
	s_add_u32 s4, s4, 0x12080ec0
	v_lshlrev_b32_e32 v146, 3, v226
	v_mov_b32_e32 v147, v0
	v_ashrrev_i32_e32 v153, 31, v152
	v_mul_u32_u24_e32 v227, 0x90, v222
	v_lshlrev_b32_e32 v228, 1, v115
	v_mul_u32_u24_e32 v229, 0x140, v1
	v_lshlrev_b32_e32 v231, 4, v6
	v_or_b32_e32 v162, s1, v222
	v_mov_b32_e32 v163, s12
	v_and_b32_e32 v164, 4, v144
	v_mov_b32_e32 v141, v140
	v_lshl_add_u64 v[198:199], s[36:37], 0, v[2:3]
	s_addc_u32 s5, s5, 0
	v_lshlrev_b32_e32 v200, 1, v114
	s_branch .LBB0_577

; #define LAS __attribute__((address_space(3)))
; template <int DKA, int DKB, int DV, int MODE  >
; __device__ __forceinline__ void attn_unit(LAS unsigned char* lds, const AttSrc& s, int q0, float c, float sink_l2, const float* qg, f32x16 (&o)[DV / 32], const int tid) {
;     ...
;             LAS unsigned char* Kl = lds + (PF2 ? 0 : ((t - t_lo) & 1)) * TB; LAS unsigned char* Vl = Kl + KBYTES;
;             ATT_STORE(krA, vrA, Kl, Vl);
.LBB0_583:
	s_bitcmp1_b32 s37, 0
	s_cselect_b32 s26, 0, 0x7400
	s_add_i32 s55, s26, 0
	s_and_saveexec_b64 s[42:43], s[38:39]
	s_cbranch_execz .LBB0_585
	v_add3_u32 v1, s55, v145, v203
	s_waitcnt vmcnt(0) lgkmcnt(0)
	ds_write_b128 v1, v[128:131]

; __device__ __forceinline__ unsigned cvt_pk_bf16(float lo, float hi) { f32x2 v = {lo, hi}; bf16x2_t b = __builtin_convertvector(v, bf16x2_t); return __builtin_bit_cast(unsigned, b); }
; #define LAS __attribute__((address_space(3)))
; __device__ __forceinline__ float fexp2(float x) { return __builtin_amdgcn_exp2f(x); }
; template <int DK, int DV, int MODE> ...
;     ...
;         mx = fmaxf(mx, __shfl_xor(mx, 32));
;         const float m_new = fmaxf(m, mx), m_use = (m_new == -INFINITY) ? 0.f : m_new;
;         const float alpha = fexp2(m - m_use);
;         float ls = 0.f;
; #pragma unroll
;         for (int i = 0; i < 16; ++i) { p0[i] = fexp2(p0[i] - m_use); p1[i] = fexp2(p1[i] - m_use); ls += p0[i] + p1[i]; }
;         l = l * alpha + ls; m = m_new;
; #pragma unroll
;         for (int d = 0; d < DV / 32; ++d)
; #pragma unroll
;             for (int i = 0; i < 16; ++i) o[d][i] *= alpha;
;         bf16x8 pb[4];
; #pragma unroll
;         for (int sx = 0; sx < 2; ++sx) {
;             u32x4 w0, w1;
;             w0.x = cvt_pk_bf16(p0[8 * sx + 0], p0[8 * sx + 1]); w0.y = cvt_pk_bf16(p0[8 * sx + 2], p0[8 * sx + 3]); w0.z = cvt_pk_bf16(p0[8 * sx + 4], p0[8 * sx + 5]); w0.w = cvt_pk_bf16(p0[8 * sx + 6], p0[8 * sx + 7]);
;             w1.x = cvt_pk_bf16(p1[8 * sx + 0], p1[8 * sx + 1]); w1.y = cvt_pk_bf16(p1[8 * sx + 2], p1[8 * sx + 3]); w1.z = cvt_pk_bf16(p1[8 * sx + 4], p1[8 * sx + 5]); w1.w = cvt_pk_bf16(p1[8 * sx + 6], p1[8 * sx + 7]);
;             pb[sx] = __builtin_bit_cast(bf16x8, w0); pb[2 + sx] = __builtin_bit_cast(bf16x8, w1);
;         }
; #pragma unroll
;         for (int d = 0; d < DV / 32; ++d)
; #pragma unroll
;             for (int t4 = 0; t4 < 4; ++t4) {
;                 const LAS unsigned char* vp_ = Vl + (16 * t4 + 4 * h + ((r & 15) >> 2)) * VSTR + (32 * d + 16 * (r >> 4) + 4 * (r & 3)) * 2;
;                 const s16x4 lo = __builtin_bit_cast(s16x4, __builtin_amdgcn_ds_read_tr16_b64_v4i16((LAS v4i16_t*)vp_));
;                 const s16x4 hi = __builtin_bit_cast(s16x4, __builtin_amdgcn_ds_read_tr16_b64_v4i16((LAS v4i16_t*)(vp_ + 8 * VSTR)));
;                 const bf16x8 vf = __builtin_shufflevector(lo, hi, 0, 1, 2, 3, 4, 5, 6, 7);
;                 o[d] = MFMA32(vf, pb[t4], o[d]);
;                 if (DV > 64 && t4 == 3) __builtin_amdgcn_sched_barrier(0);
;             }
.Ljoin_nm2:
	ds_bpermute_b32 v4, v165, v1
	s_waitcnt lgkmcnt(0)
	v_max3_f32 v1, v237, v1, v4
	v_cmp_neq_f32_e32 vcc, s88, v1
	s_nop 1
	v_cndmask_b32_e32 v111, 0, v1, vcc
	v_sub_f32_e32 v2, v2, v111
	v_exp_f32_e32 v241, v2
	v_sub_f32_e32 v2, v3, v111
	v_exp_f32_e32 v244, v2
	v_sub_f32_e32 v2, v5, v111
	v_exp_f32_e32 v4, v2
	v_sub_f32_e32 v2, v6, v111
	v_exp_f32_e32 v2, v2
	v_add_f32_e32 v3, v244, v241
	v_mov_b32_e32 v5, v0
	v_sub_f32_e32 v237, v237, v111
	v_pk_add_f32 v[6:7], v[2:3], v[4:5]
	v_sub_f32_e32 v3, v9, v111
	v_pk_add_f32 v[6:7], v[6:7], v[6:7] op_sel_hi:[0,1]
	v_sub_f32_e32 v5, v8, v111
	v_exp_f32_e32 v3, v3
	v_exp_f32_e32 v5, v5
	v_sub_f32_e32 v6, v10, v111
	v_sub_f32_e32 v8, v11, v111
	v_exp_f32_e32 v6, v6
	v_exp_f32_e32 v8, v8
	v_add_f32_e32 v9, v5, v3
	v_pk_add_f32 v[10:11], v[8:9], v[6:7]
	s_nop 0
	v_pk_add_f32 v[12:13], v[10:11], v[10:11] op_sel_hi:[0,1]
	v_sub_f32_e32 v7, v15, v111
	v_sub_f32_e32 v9, v14, v111
	v_sub_f32_e32 v10, v82, v111
	v_exp_f32_e32 v7, v7
	v_exp_f32_e32 v9, v9
	v_exp_f32_e32 v12, v10
	v_sub_f32_e32 v10, v80, v111
	v_exp_f32_e32 v80, v10
	v_add_f32_e32 v81, v9, v7
	v_pk_add_f32 v[10:11], v[80:81], v[12:13]
	s_nop 0
	v_pk_add_f32 v[88:89], v[10:11], v[10:11] op_sel_hi:[0,1]
	v_sub_f32_e32 v10, v84, v111
	v_exp_f32_e32 v13, v10
	v_sub_f32_e32 v10, v83, v111
	v_exp_f32_e32 v81, v10
	v_sub_f32_e32 v10, v86, v111
	v_exp_f32_e32 v88, v10
	v_sub_f32_e32 v10, v85, v111
	v_exp_f32_e32 v90, v10
	v_add_f32_e32 v91, v81, v13
	v_cvt_pk_bf16_f32 v12, v7, v12
	v_cvt_pk_bf16_f32 v13, v13, v88
	v_pk_add_f32 v[10:11], v[90:91], v[88:89]
	v_cvt_pk_bf16_f32 v7, v5, v8
	v_pk_add_f32 v[14:15], v[10:11], v[10:11] op_sel_hi:[0,1]
	v_sub_f32_e32 v10, v96, v111
	v_exp_f32_e32 v245, v10
	v_sub_f32_e32 v10, v87, v111
	v_exp_f32_e32 v89, v10
	v_sub_f32_e32 v10, v98, v111
	v_exp_f32_e32 v14, v10
	v_sub_f32_e32 v10, v97, v111
	v_exp_f32_e32 v92, v10
	v_add_f32_e32 v93, v89, v245
	v_cvt_pk_bf16_f32 v8, v9, v80
	v_cvt_pk_bf16_f32 v9, v81, v90
	v_pk_add_f32 v[10:11], v[92:93], v[14:15]
	v_cvt_pk_bf16_f32 v80, v245, v14
	v_pk_add_f32 v[82:83], v[10:11], v[10:11] op_sel_hi:[0,1]
	v_sub_f32_e32 v10, v100, v111
	v_exp_f32_e32 v93, v10
	v_sub_f32_e32 v10, v99, v111
	v_exp_f32_e32 v91, v10
	v_sub_f32_e32 v10, v102, v111
	v_exp_f32_e32 v82, v10
	v_sub_f32_e32 v10, v101, v111
	v_exp_f32_e32 v94, v10
	v_add_f32_e32 v95, v91, v93
	v_cvt_pk_bf16_f32 v81, v93, v82
	v_pk_add_f32 v[10:11], v[94:95], v[82:83]
	s_nop 0
	v_pk_add_f32 v[84:85], v[10:11], v[10:11] op_sel_hi:[0,1]
	v_sub_f32_e32 v10, v104, v111
	v_exp_f32_e32 v83, v10
	v_sub_f32_e32 v10, v103, v111
	v_exp_f32_e32 v95, v10
	v_sub_f32_e32 v10, v106, v111
	v_exp_f32_e32 v84, v10
	v_sub_f32_e32 v10, v105, v111
	v_exp_f32_e32 v96, v10
	v_add_f32_e32 v97, v95, v83
	v_cvt_pk_bf16_f32 v82, v83, v84
	v_pk_add_f32 v[10:11], v[96:97], v[84:85]
	s_nop 0
	v_pk_add_f32 v[86:87], v[10:11], v[10:11] op_sel_hi:[0,1]
	v_sub_f32_e32 v10, v108, v111
	v_exp_f32_e32 v85, v10
	v_sub_f32_e32 v10, v107, v111
	v_exp_f32_e32 v97, v10
	v_sub_f32_e32 v10, v110, v111
	v_exp_f32_e32 v86, v10
	v_sub_f32_e32 v10, v109, v111
	v_exp_f32_e32 v98, v10
	v_add_f32_e32 v99, v97, v85
	v_cvt_pk_bf16_f32 v83, v85, v86
	v_pk_add_f32 v[10:11], v[98:99], v[86:87]
	s_nop 0
	v_add_f32_e32 v15, v10, v11
	v_exp_f32_e32 v10, v237
	v_cvt_pk_bf16_f32 v5, v97, v98
	v_pk_mul_f32 v[78:79], v[78:79], v[10:11] op_sel_hi:[1,0]
	v_pk_mul_f32 v[76:77], v[76:77], v[10:11] op_sel_hi:[1,0]
	v_pk_mul_f32 v[74:75], v[74:75], v[10:11] op_sel_hi:[1,0]
	v_pk_mul_f32 v[72:73], v[72:73], v[10:11] op_sel_hi:[1,0]
	v_pk_mul_f32 v[70:71], v[70:71], v[10:11] op_sel_hi:[1,0]
	v_pk_mul_f32 v[68:69], v[68:69], v[10:11] op_sel_hi:[1,0]
	v_pk_mul_f32 v[66:67], v[66:67], v[10:11] op_sel_hi:[1,0]
	v_pk_mul_f32 v[64:65], v[64:65], v[10:11] op_sel_hi:[1,0]
	v_pk_mul_f32 v[62:63], v[62:63], v[10:11] op_sel_hi:[1,0]
	v_pk_mul_f32 v[60:61], v[60:61], v[10:11] op_sel_hi:[1,0]
	v_pk_mul_f32 v[58:59], v[58:59], v[10:11] op_sel_hi:[1,0]
	v_pk_mul_f32 v[56:57], v[56:57], v[10:11] op_sel_hi:[1,0]
	v_pk_mul_f32 v[54:55], v[54:55], v[10:11] op_sel_hi:[1,0]
	v_pk_mul_f32 v[52:53], v[52:53], v[10:11] op_sel_hi:[1,0]
	v_pk_mul_f32 v[50:51], v[50:51], v[10:11] op_sel_hi:[1,0]
	v_pk_mul_f32 v[48:49], v[48:49], v[10:11] op_sel_hi:[1,0]
	v_pk_mul_f32 v[46:47], v[46:47], v[10:11] op_sel_hi:[1,0]
	v_pk_mul_f32 v[44:45], v[44:45], v[10:11] op_sel_hi:[1,0]
	v_pk_mul_f32 v[42:43], v[42:43], v[10:11] op_sel_hi:[1,0]
	v_pk_mul_f32 v[40:41], v[40:41], v[10:11] op_sel_hi:[1,0]
	v_pk_mul_f32 v[38:39], v[38:39], v[10:11] op_sel_hi:[1,0]
	v_pk_mul_f32 v[36:37], v[36:37], v[10:11] op_sel_hi:[1,0]
	v_pk_mul_f32 v[34:35], v[34:35], v[10:11] op_sel_hi:[1,0]
	v_pk_mul_f32 v[32:33], v[32:33], v[10:11] op_sel_hi:[1,0]
	v_pk_mul_f32 v[30:31], v[30:31], v[10:11] op_sel_hi:[1,0]
	v_pk_mul_f32 v[28:29], v[28:29], v[10:11] op_sel_hi:[1,0]
	v_pk_mul_f32 v[26:27], v[26:27], v[10:11] op_sel_hi:[1,0]
	v_pk_mul_f32 v[24:25], v[24:25], v[10:11] op_sel_hi:[1,0]
	v_pk_mul_f32 v[22:23], v[22:23], v[10:11] op_sel_hi:[1,0]
	v_pk_mul_f32 v[20:21], v[20:21], v[10:11] op_sel_hi:[1,0]
	v_pk_mul_f32 v[18:19], v[18:19], v[10:11] op_sel_hi:[1,0]
	v_pk_mul_f32 v[16:17], v[16:17], v[10:11] op_sel_hi:[1,0]
	v_cvt_pk_bf16_f32 v11, v3, v6
	v_cvt_pk_bf16_f32 v6, v244, v2
	v_cvt_pk_bf16_f32 v2, v89, v92
	v_add3_u32 v92, s55, v228, v229
	v_cvt_pk_bf16_f32 v3, v91, v94
	v_fmac_f32_e32 v15, v235, v10
	v_cvt_pk_bf16_f32 v10, v241, v4
	v_cvt_pk_bf16_f32 v4, v95, v96
	ds_read_b64_tr_b16 v[84:85], v92 offset:9216
	ds_read_b64_tr_b16 v[86:87], v92 offset:11776
	ds_read_b64_tr_b16 v[88:89], v92 offset:14336
	ds_read_b64_tr_b16 v[90:91], v92 offset:16896
	ds_read_b64_tr_b16 v[94:95], v92 offset:19456
	ds_read_b64_tr_b16 v[96:97], v92 offset:22016
	ds_read_b64_tr_b16 v[98:99], v92 offset:24576
	ds_read_b64_tr_b16 v[100:101], v92 offset:27136
	s_waitcnt lgkmcnt(6)
; #define LAS __attribute__((address_space(3)))
; #define MFMA32(a, b, c) __builtin_amdgcn_mfma_f32_32x32x16_bf16((a), (b), (c), 0, 0, 0)
; template <int DK, int DV, int MODE> ...
;     ...
; #pragma unroll
;         for (int d = 0; d < DV / 32; ++d)
; #pragma unroll
;             for (int t4 = 0; t4 < 4; ++t4) {
;                 const LAS unsigned char* vp_ = Vl + (16 * t4 + 4 * h + ((r & 15) >> 2)) * VSTR + (32 * d + 16 * (r >> 4) + 4 * (r & 3)) * 2;
;                 const s16x4 lo = __builtin_bit_cast(s16x4, __builtin_amdgcn_ds_read_tr16_b64_v4i16((LAS v4i16_t*)vp_));
;                 const s16x4 hi = __builtin_bit_cast(s16x4, __builtin_amdgcn_ds_read_tr16_b64_v4i16((LAS v4i16_t*)(vp_ + 8 * VSTR)));
;                 const bf16x8 vf = __builtin_shufflevector(lo, hi, 0, 1, 2, 3, 4, 5, 6, 7);
;                 o[d] = MFMA32(vf, pb[t4], o[d]);
;                 if (DV > 64 && t4 == 3) __builtin_amdgcn_sched_barrier(0);
;             }
	v_mfma_f32_32x32x16_bf16 v[64:79], v[84:87], v[10:13], v[64:79]
	ds_read_b64_tr_b16 v[84:85], v92 offset:9280
	ds_read_b64_tr_b16 v[86:87], v92 offset:11840
	s_waitcnt lgkmcnt(6)
	v_mfma_f32_32x32x16_bf16 v[64:79], v[88:91], v[80:83], v[64:79]
	ds_read_b64_tr_b16 v[88:89], v92 offset:14400
	ds_read_b64_tr_b16 v[90:91], v92 offset:16960
	s_waitcnt lgkmcnt(6)
	v_mfma_f32_32x32x16_bf16 v[64:79], v[94:97], v[6:9], v[64:79]
	ds_read_b64_tr_b16 v[94:95], v92 offset:19520
	ds_read_b64_tr_b16 v[96:97], v92 offset:22080
	s_waitcnt lgkmcnt(6)
	v_mfma_f32_32x32x16_bf16 v[64:79], v[98:101], v[2:5], v[64:79]
	ds_read_b64_tr_b16 v[98:99], v92 offset:24640
	ds_read_b64_tr_b16 v[100:101], v92 offset:27200
	s_waitcnt lgkmcnt(6)
	v_mfma_f32_32x32x16_bf16 v[48:63], v[84:87], v[10:13], v[48:63]
	ds_read_b64_tr_b16 v[84:85], v92 offset:9344
	ds_read_b64_tr_b16 v[86:87], v92 offset:11904
	s_waitcnt lgkmcnt(6)
	v_mfma_f32_32x32x16_bf16 v[48:63], v[88:91], v[80:83], v[48:63]
	ds_read_b64_tr_b16 v[88:89], v92 offset:14464
	ds_read_b64_tr_b16 v[90:91], v92 offset:17024
	s_waitcnt lgkmcnt(6)
	v_mfma_f32_32x32x16_bf16 v[48:63], v[94:97], v[6:9], v[48:63]
	ds_read_b64_tr_b16 v[94:95], v92 offset:19584
	ds_read_b64_tr_b16 v[96:97], v92 offset:22144
	s_waitcnt lgkmcnt(6)
	v_mfma_f32_32x32x16_bf16 v[48:63], v[98:101], v[2:5], v[48:63]
	ds_read_b64_tr_b16 v[98:99], v92 offset:24704
	ds_read_b64_tr_b16 v[100:101], v92 offset:27264
	s_waitcnt lgkmcnt(6)
	v_mfma_f32_32x32x16_bf16 v[32:47], v[84:87], v[10:13], v[32:47]
	ds_read_b64_tr_b16 v[84:85], v92 offset:9408
	ds_read_b64_tr_b16 v[86:87], v92 offset:11968
	s_waitcnt lgkmcnt(6)
	v_mfma_f32_32x32x16_bf16 v[32:47], v[88:91], v[80:83], v[32:47]
	ds_read_b64_tr_b16 v[88:89], v92 offset:14528
	ds_read_b64_tr_b16 v[90:91], v92 offset:17088
	s_waitcnt lgkmcnt(6)
	v_mfma_f32_32x32x16_bf16 v[32:47], v[94:97], v[6:9], v[32:47]
	ds_read_b64_tr_b16 v[94:95], v92 offset:19648
	ds_read_b64_tr_b16 v[96:97], v92 offset:22208
	s_waitcnt lgkmcnt(6)
	v_mfma_f32_32x32x16_bf16 v[32:47], v[98:101], v[2:5], v[32:47]
	ds_read_b64_tr_b16 v[98:99], v92 offset:24768
	ds_read_b64_tr_b16 v[100:101], v92 offset:27328
	s_waitcnt lgkmcnt(6)
	v_mfma_f32_32x32x16_bf16 v[16:31], v[84:87], v[10:13], v[16:31]
	s_waitcnt lgkmcnt(4)
	v_mfma_f32_32x32x16_bf16 v[16:31], v[88:91], v[80:83], v[16:31]
	s_waitcnt lgkmcnt(2)
	v_mfma_f32_32x32x16_bf16 v[16:31], v[94:97], v[6:9], v[16:31]
	s_waitcnt lgkmcnt(0)
	v_mfma_f32_32x32x16_bf16 v[16:31], v[98:101], v[2:5], v[16:31]
	v_mov_b32_e32 v237, v1
	v_mov_b32_e32 v235, v15
	s_branch .LBB0_582

; #define LAS __attribute__((address_space(3)))
; template <int DKA, int DKB, int DV, int MODE  >
; __device__ __forceinline__ void attn_unit(LAS unsigned char* lds, const AttSrc& s, int q0, float c, float sink_l2, const float* qg, f32x16 (&o)[DV / 32], const int tid) {
;     ...
;             LAS unsigned char* Kl = lds + (PF2 ? 0 : ((t - t_lo) & 1)) * TB; LAS unsigned char* Vl = Kl + KBYTES;
;             ATT_STORE(krA, vrA, Kl, Vl);
.LBB0_597:
	s_bitcmp1_b32 s35, 0
	s_cselect_b32 s26, 0, 0x7400
	s_add_i32 s52, s26, 0
	s_and_saveexec_b64 s[42:43], s[38:39]
	s_cbranch_execz .LBB0_599
	v_add3_u32 v1, s52, v145, v203
	s_waitcnt vmcnt(0) lgkmcnt(0)
	ds_write_b128 v1, v[128:131]

; __device__ __forceinline__ unsigned cvt_pk_bf16(float lo, float hi) { f32x2 v = {lo, hi}; bf16x2_t b = __builtin_convertvector(v, bf16x2_t); return __builtin_bit_cast(unsigned, b); }
; #define LAS __attribute__((address_space(3)))
; __device__ __forceinline__ float fexp2(float x) { return __builtin_amdgcn_exp2f(x); }
; template <int DK, int DV, int MODE> ...
;     ...
;         mx = fmaxf(mx, __shfl_xor(mx, 32));
;         const float m_new = fmaxf(m, mx), m_use = (m_new == -INFINITY) ? 0.f : m_new;
;         const float alpha = fexp2(m - m_use);
;         float ls = 0.f;
; #pragma unroll
;         for (int i = 0; i < 16; ++i) { p0[i] = fexp2(p0[i] - m_use); p1[i] = fexp2(p1[i] - m_use); ls += p0[i] + p1[i]; }
;         l = l * alpha + ls; m = m_new;
; #pragma unroll
;         for (int d = 0; d < DV / 32; ++d)
; #pragma unroll
;             for (int i = 0; i < 16; ++i) o[d][i] *= alpha;
;         bf16x8 pb[4];
; #pragma unroll
;         for (int sx = 0; sx < 2; ++sx) {
;             u32x4 w0, w1;
;             w0.x = cvt_pk_bf16(p0[8 * sx + 0], p0[8 * sx + 1]); w0.y = cvt_pk_bf16(p0[8 * sx + 2], p0[8 * sx + 3]); w0.z = cvt_pk_bf16(p0[8 * sx + 4], p0[8 * sx + 5]); w0.w = cvt_pk_bf16(p0[8 * sx + 6], p0[8 * sx + 7]);
;             w1.x = cvt_pk_bf16(p1[8 * sx + 0], p1[8 * sx + 1]); w1.y = cvt_pk_bf16(p1[8 * sx + 2], p1[8 * sx + 3]); w1.z = cvt_pk_bf16(p1[8 * sx + 4], p1[8 * sx + 5]); w1.w = cvt_pk_bf16(p1[8 * sx + 6], p1[8 * sx + 7]);
;             pb[sx] = __builtin_bit_cast(bf16x8, w0); pb[2 + sx] = __builtin_bit_cast(bf16x8, w1);
;         }
; #pragma unroll
;         for (int d = 0; d < DV / 32; ++d)
; #pragma unroll
;             for (int t4 = 0; t4 < 4; ++t4) {
;                 const LAS unsigned char* vp_ = Vl + (16 * t4 + 4 * h + ((r & 15) >> 2)) * VSTR + (32 * d + 16 * (r >> 4) + 4 * (r & 3)) * 2;
;                 const s16x4 lo = __builtin_bit_cast(s16x4, __builtin_amdgcn_ds_read_tr16_b64_v4i16((LAS v4i16_t*)vp_));
;                 const s16x4 hi = __builtin_bit_cast(s16x4, __builtin_amdgcn_ds_read_tr16_b64_v4i16((LAS v4i16_t*)(vp_ + 8 * VSTR)));
;                 const bf16x8 vf = __builtin_shufflevector(lo, hi, 0, 1, 2, 3, 4, 5, 6, 7);
;                 o[d] = MFMA32(vf, pb[t4], o[d]);
;                 if (DV > 64 && t4 == 3) __builtin_amdgcn_sched_barrier(0);
;             }
.Ljoin_nm3:
	ds_bpermute_b32 v4, v165, v1
	s_waitcnt lgkmcnt(0)
	v_max3_f32 v1, v211, v1, v4
	v_cmp_neq_f32_e32 vcc, s88, v1
	s_nop 1
	v_cndmask_b32_e32 v111, 0, v1, vcc
	v_sub_f32_e32 v2, v2, v111
	v_exp_f32_e32 v212, v2
	v_sub_f32_e32 v2, v3, v111
	v_exp_f32_e32 v213, v2
	v_sub_f32_e32 v2, v5, v111
	v_exp_f32_e32 v4, v2
	v_sub_f32_e32 v2, v6, v111
	v_exp_f32_e32 v2, v2
	v_add_f32_e32 v3, v213, v212
	v_mov_b32_e32 v5, v0
	v_sub_f32_e32 v211, v211, v111
	v_pk_add_f32 v[6:7], v[2:3], v[4:5]
	v_sub_f32_e32 v3, v9, v111
	v_pk_add_f32 v[6:7], v[6:7], v[6:7] op_sel_hi:[0,1]
	v_sub_f32_e32 v5, v8, v111
	v_exp_f32_e32 v3, v3
	v_exp_f32_e32 v5, v5
	v_sub_f32_e32 v6, v10, v111
	v_sub_f32_e32 v8, v11, v111
	v_exp_f32_e32 v6, v6
	v_exp_f32_e32 v8, v8
	v_add_f32_e32 v9, v5, v3
	v_pk_add_f32 v[10:11], v[8:9], v[6:7]
	s_nop 0
	v_pk_add_f32 v[12:13], v[10:11], v[10:11] op_sel_hi:[0,1]
	v_sub_f32_e32 v7, v15, v111
	v_sub_f32_e32 v9, v14, v111
	v_sub_f32_e32 v10, v82, v111
	v_exp_f32_e32 v7, v7
	v_exp_f32_e32 v9, v9
	v_exp_f32_e32 v12, v10
	v_sub_f32_e32 v10, v80, v111
	v_exp_f32_e32 v80, v10
	v_add_f32_e32 v81, v9, v7
	v_pk_add_f32 v[10:11], v[80:81], v[12:13]
	s_nop 0
	v_pk_add_f32 v[88:89], v[10:11], v[10:11] op_sel_hi:[0,1]
	v_sub_f32_e32 v10, v84, v111
	v_exp_f32_e32 v13, v10
	v_sub_f32_e32 v10, v83, v111
	v_exp_f32_e32 v81, v10
	v_sub_f32_e32 v10, v86, v111
	v_exp_f32_e32 v88, v10
	v_sub_f32_e32 v10, v85, v111
	v_exp_f32_e32 v90, v10
	v_add_f32_e32 v91, v81, v13
	v_cvt_pk_bf16_f32 v12, v7, v12
	v_cvt_pk_bf16_f32 v13, v13, v88
	v_pk_add_f32 v[10:11], v[90:91], v[88:89]
	v_cvt_pk_bf16_f32 v7, v5, v8
	v_pk_add_f32 v[14:15], v[10:11], v[10:11] op_sel_hi:[0,1]
	v_sub_f32_e32 v10, v96, v111
	v_exp_f32_e32 v214, v10
	v_sub_f32_e32 v10, v87, v111
	v_exp_f32_e32 v89, v10
	v_sub_f32_e32 v10, v98, v111
	v_exp_f32_e32 v14, v10
	v_sub_f32_e32 v10, v97, v111
	v_exp_f32_e32 v92, v10
	v_add_f32_e32 v93, v89, v214
	v_cvt_pk_bf16_f32 v8, v9, v80
	v_cvt_pk_bf16_f32 v9, v81, v90
	v_pk_add_f32 v[10:11], v[92:93], v[14:15]
	v_cvt_pk_bf16_f32 v80, v214, v14
	v_pk_add_f32 v[82:83], v[10:11], v[10:11] op_sel_hi:[0,1]
	v_sub_f32_e32 v10, v100, v111
	v_exp_f32_e32 v93, v10
	v_sub_f32_e32 v10, v99, v111
	v_exp_f32_e32 v91, v10
	v_sub_f32_e32 v10, v102, v111
	v_exp_f32_e32 v82, v10
	v_sub_f32_e32 v10, v101, v111
	v_exp_f32_e32 v94, v10
	v_add_f32_e32 v95, v91, v93
	v_cvt_pk_bf16_f32 v81, v93, v82
	v_pk_add_f32 v[10:11], v[94:95], v[82:83]
	s_nop 0
	v_pk_add_f32 v[84:85], v[10:11], v[10:11] op_sel_hi:[0,1]
	v_sub_f32_e32 v10, v104, v111
	v_exp_f32_e32 v83, v10
	v_sub_f32_e32 v10, v103, v111
	v_exp_f32_e32 v95, v10
	v_sub_f32_e32 v10, v106, v111
	v_exp_f32_e32 v84, v10
	v_sub_f32_e32 v10, v105, v111
	v_exp_f32_e32 v96, v10
	v_add_f32_e32 v97, v95, v83
	v_cvt_pk_bf16_f32 v82, v83, v84
	v_pk_add_f32 v[10:11], v[96:97], v[84:85]
	s_nop 0
	v_pk_add_f32 v[86:87], v[10:11], v[10:11] op_sel_hi:[0,1]
	v_sub_f32_e32 v10, v108, v111
	v_exp_f32_e32 v85, v10
	v_sub_f32_e32 v10, v107, v111
	v_exp_f32_e32 v97, v10
	v_sub_f32_e32 v10, v110, v111
	v_exp_f32_e32 v86, v10
	v_sub_f32_e32 v10, v109, v111
	v_exp_f32_e32 v98, v10
	v_add_f32_e32 v99, v97, v85
	v_cvt_pk_bf16_f32 v83, v85, v86
	v_pk_add_f32 v[10:11], v[98:99], v[86:87]
	s_nop 0
	v_add_f32_e32 v15, v10, v11
	v_exp_f32_e32 v10, v211
	v_cvt_pk_bf16_f32 v5, v97, v98
	v_pk_mul_f32 v[78:79], v[78:79], v[10:11] op_sel_hi:[1,0]
	v_pk_mul_f32 v[76:77], v[76:77], v[10:11] op_sel_hi:[1,0]
	v_pk_mul_f32 v[74:75], v[74:75], v[10:11] op_sel_hi:[1,0]
	v_pk_mul_f32 v[72:73], v[72:73], v[10:11] op_sel_hi:[1,0]
	v_pk_mul_f32 v[70:71], v[70:71], v[10:11] op_sel_hi:[1,0]
	v_pk_mul_f32 v[68:69], v[68:69], v[10:11] op_sel_hi:[1,0]
	v_pk_mul_f32 v[66:67], v[66:67], v[10:11] op_sel_hi:[1,0]
	v_pk_mul_f32 v[64:65], v[64:65], v[10:11] op_sel_hi:[1,0]
	v_pk_mul_f32 v[62:63], v[62:63], v[10:11] op_sel_hi:[1,0]
	v_pk_mul_f32 v[60:61], v[60:61], v[10:11] op_sel_hi:[1,0]
	v_pk_mul_f32 v[58:59], v[58:59], v[10:11] op_sel_hi:[1,0]
	v_pk_mul_f32 v[56:57], v[56:57], v[10:11] op_sel_hi:[1,0]
	v_pk_mul_f32 v[54:55], v[54:55], v[10:11] op_sel_hi:[1,0]
	v_pk_mul_f32 v[52:53], v[52:53], v[10:11] op_sel_hi:[1,0]
	v_pk_mul_f32 v[50:51], v[50:51], v[10:11] op_sel_hi:[1,0]
	v_pk_mul_f32 v[48:49], v[48:49], v[10:11] op_sel_hi:[1,0]
	v_pk_mul_f32 v[46:47], v[46:47], v[10:11] op_sel_hi:[1,0]
	v_pk_mul_f32 v[44:45], v[44:45], v[10:11] op_sel_hi:[1,0]
	v_pk_mul_f32 v[42:43], v[42:43], v[10:11] op_sel_hi:[1,0]
	v_pk_mul_f32 v[40:41], v[40:41], v[10:11] op_sel_hi:[1,0]
	v_pk_mul_f32 v[38:39], v[38:39], v[10:11] op_sel_hi:[1,0]
	v_pk_mul_f32 v[36:37], v[36:37], v[10:11] op_sel_hi:[1,0]
	v_pk_mul_f32 v[34:35], v[34:35], v[10:11] op_sel_hi:[1,0]
	v_pk_mul_f32 v[32:33], v[32:33], v[10:11] op_sel_hi:[1,0]
	v_pk_mul_f32 v[30:31], v[30:31], v[10:11] op_sel_hi:[1,0]
	v_pk_mul_f32 v[28:29], v[28:29], v[10:11] op_sel_hi:[1,0]
	v_pk_mul_f32 v[26:27], v[26:27], v[10:11] op_sel_hi:[1,0]
	v_pk_mul_f32 v[24:25], v[24:25], v[10:11] op_sel_hi:[1,0]
	v_pk_mul_f32 v[22:23], v[22:23], v[10:11] op_sel_hi:[1,0]
	v_pk_mul_f32 v[20:21], v[20:21], v[10:11] op_sel_hi:[1,0]
	v_pk_mul_f32 v[18:19], v[18:19], v[10:11] op_sel_hi:[1,0]
	v_pk_mul_f32 v[16:17], v[16:17], v[10:11] op_sel_hi:[1,0]
	v_cvt_pk_bf16_f32 v11, v3, v6
	v_cvt_pk_bf16_f32 v6, v213, v2
	v_cvt_pk_bf16_f32 v2, v89, v92
	v_add3_u32 v92, s52, v228, v229
	v_cvt_pk_bf16_f32 v3, v91, v94
	v_fmac_f32_e32 v15, v210, v10
	v_cvt_pk_bf16_f32 v10, v212, v4
	v_cvt_pk_bf16_f32 v4, v95, v96
	ds_read_b64_tr_b16 v[84:85], v92 offset:9216
	ds_read_b64_tr_b16 v[86:87], v92 offset:11776
	ds_read_b64_tr_b16 v[88:89], v92 offset:14336
	ds_read_b64_tr_b16 v[90:91], v92 offset:16896
	ds_read_b64_tr_b16 v[94:95], v92 offset:19456
	ds_read_b64_tr_b16 v[96:97], v92 offset:22016
	ds_read_b64_tr_b16 v[98:99], v92 offset:24576
	ds_read_b64_tr_b16 v[100:101], v92 offset:27136
	s_waitcnt lgkmcnt(6)
; #define LAS __attribute__((address_space(3)))
; #define MFMA32(a, b, c) __builtin_amdgcn_mfma_f32_32x32x16_bf16((a), (b), (c), 0, 0, 0)
; template <int DK, int DV, int MODE> ...
;     ...
; #pragma unroll
;         for (int d = 0; d < DV / 32; ++d)
; #pragma unroll
;             for (int t4 = 0; t4 < 4; ++t4) {
;                 const LAS unsigned char* vp_ = Vl + (16 * t4 + 4 * h + ((r & 15) >> 2)) * VSTR + (32 * d + 16 * (r >> 4) + 4 * (r & 3)) * 2;
;                 const s16x4 lo = __builtin_bit_cast(s16x4, __builtin_amdgcn_ds_read_tr16_b64_v4i16((LAS v4i16_t*)vp_));
;                 const s16x4 hi = __builtin_bit_cast(s16x4, __builtin_amdgcn_ds_read_tr16_b64_v4i16((LAS v4i16_t*)(vp_ + 8 * VSTR)));
;                 const bf16x8 vf = __builtin_shufflevector(lo, hi, 0, 1, 2, 3, 4, 5, 6, 7);
;                 o[d] = MFMA32(vf, pb[t4], o[d]);
;                 if (DV > 64 && t4 == 3) __builtin_amdgcn_sched_barrier(0);
;             }
	v_mfma_f32_32x32x16_bf16 v[64:79], v[84:87], v[10:13], v[64:79]
	ds_read_b64_tr_b16 v[84:85], v92 offset:9280
	ds_read_b64_tr_b16 v[86:87], v92 offset:11840
	s_waitcnt lgkmcnt(6)
	v_mfma_f32_32x32x16_bf16 v[64:79], v[88:91], v[80:83], v[64:79]
	ds_read_b64_tr_b16 v[88:89], v92 offset:14400
	ds_read_b64_tr_b16 v[90:91], v92 offset:16960
	s_waitcnt lgkmcnt(6)
	v_mfma_f32_32x32x16_bf16 v[64:79], v[94:97], v[6:9], v[64:79]
	ds_read_b64_tr_b16 v[94:95], v92 offset:19520
	ds_read_b64_tr_b16 v[96:97], v92 offset:22080
	s_waitcnt lgkmcnt(6)
	v_mfma_f32_32x32x16_bf16 v[64:79], v[98:101], v[2:5], v[64:79]
	ds_read_b64_tr_b16 v[98:99], v92 offset:24640
	ds_read_b64_tr_b16 v[100:101], v92 offset:27200
	s_waitcnt lgkmcnt(6)
	v_mfma_f32_32x32x16_bf16 v[48:63], v[84:87], v[10:13], v[48:63]
	ds_read_b64_tr_b16 v[84:85], v92 offset:9344
	ds_read_b64_tr_b16 v[86:87], v92 offset:11904
	s_waitcnt lgkmcnt(6)
	v_mfma_f32_32x32x16_bf16 v[48:63], v[88:91], v[80:83], v[48:63]
	ds_read_b64_tr_b16 v[88:89], v92 offset:14464
	ds_read_b64_tr_b16 v[90:91], v92 offset:17024
	s_waitcnt lgkmcnt(6)
	v_mfma_f32_32x32x16_bf16 v[48:63], v[94:97], v[6:9], v[48:63]
	ds_read_b64_tr_b16 v[94:95], v92 offset:19584
	ds_read_b64_tr_b16 v[96:97], v92 offset:22144
	s_waitcnt lgkmcnt(6)
	v_mfma_f32_32x32x16_bf16 v[48:63], v[98:101], v[2:5], v[48:63]
	ds_read_b64_tr_b16 v[98:99], v92 offset:24704
	ds_read_b64_tr_b16 v[100:101], v92 offset:27264
	s_waitcnt lgkmcnt(6)
	v_mfma_f32_32x32x16_bf16 v[32:47], v[84:87], v[10:13], v[32:47]
	ds_read_b64_tr_b16 v[84:85], v92 offset:9408
	ds_read_b64_tr_b16 v[86:87], v92 offset:11968
	s_waitcnt lgkmcnt(6)
	v_mfma_f32_32x32x16_bf16 v[32:47], v[88:91], v[80:83], v[32:47]
	ds_read_b64_tr_b16 v[88:89], v92 offset:14528
	ds_read_b64_tr_b16 v[90:91], v92 offset:17088
	s_waitcnt lgkmcnt(6)
	v_mfma_f32_32x32x16_bf16 v[32:47], v[94:97], v[6:9], v[32:47]
	ds_read_b64_tr_b16 v[94:95], v92 offset:19648
	ds_read_b64_tr_b16 v[96:97], v92 offset:22208
	s_waitcnt lgkmcnt(6)
	v_mfma_f32_32x32x16_bf16 v[32:47], v[98:101], v[2:5], v[32:47]
	ds_read_b64_tr_b16 v[98:99], v92 offset:24768
	ds_read_b64_tr_b16 v[100:101], v92 offset:27328
	s_waitcnt lgkmcnt(6)
	v_mfma_f32_32x32x16_bf16 v[16:31], v[84:87], v[10:13], v[16:31]
	s_waitcnt lgkmcnt(4)
	v_mfma_f32_32x32x16_bf16 v[16:31], v[88:91], v[80:83], v[16:31]
	s_waitcnt lgkmcnt(2)
	v_mfma_f32_32x32x16_bf16 v[16:31], v[94:97], v[6:9], v[16:31]
	s_waitcnt lgkmcnt(0)
	v_mfma_f32_32x32x16_bf16 v[16:31], v[98:101], v[2:5], v[16:31]
	v_mov_b32_e32 v211, v1
	v_mov_b32_e32 v210, v15
	s_branch .LBB0_596
